# gemm_small (P3,P6,P7 sample-row GEMMs): all 16 fragment loads issued up front into dead VGPRs with counted vmcnt, instead of 7 loads + drain + trickled pairs
# speedup vs baseline: 1.0135x; 1.0099x over previous
.LBB0_801:
	s_and_b32 s10, s9, 0xffffffe0
	v_or_b32_e32 v0, s10, v230
	v_ashrrev_i32_e32 v1, 31, v0
	v_lshlrev_b64 v[0:1], 11, v[0:1]
	v_lshl_add_u64 v[50:51], v[20:21], 0, v[0:1]
	s_and_b32 s11, s13, 0xe0
	v_or_b32_e32 v28, s11, v230
	v_lshlrev_b32_e32 v16, 11, v28
	v_lshl_add_u64 v[52:53], v[18:19], 0, v[16:17]
	s_and_b64 vcc, exec, s[6:7]
	global_load_dwordx4 v[84:87], v[50:51], off
	global_load_dwordx4 v[88:91], v[52:53], off
	global_load_dwordx4 v[92:95], v[50:51], off offset:32
	global_load_dwordx4 v[96:99], v[52:53], off offset:32
	global_load_dwordx4 v[100:103], v[50:51], off offset:64
	global_load_dwordx4 v[104:107], v[52:53], off offset:64
	global_load_dwordx4 v[108:111], v[50:51], off offset:96
	global_load_dwordx4 v[112:115], v[52:53], off offset:96
	global_load_dwordx4 v[116:119], v[50:51], off offset:128
	global_load_dwordx4 v[120:123], v[52:53], off offset:128
	global_load_dwordx4 v[124:127], v[50:51], off offset:160
	global_load_dwordx4 v[128:131], v[52:53], off offset:160
	global_load_dwordx4 v[132:135], v[50:51], off offset:192
	global_load_dwordx4 v[152:155], v[52:53], off offset:192
	global_load_dwordx4 v[156:159], v[50:51], off offset:224
	global_load_dwordx4 v[168:171], v[52:53], off offset:224
	s_waitcnt vmcnt(14)
	v_mfma_f32_32x32x16_bf16 v[0:15], v[84:87], v[88:91], 0
	s_waitcnt vmcnt(12)
	v_mfma_f32_32x32x16_bf16 v[0:15], v[92:95], v[96:99], v[0:15]
	s_waitcnt vmcnt(10)
	v_mfma_f32_32x32x16_bf16 v[0:15], v[100:103], v[104:107], v[0:15]
	s_waitcnt vmcnt(8)
	v_mfma_f32_32x32x16_bf16 v[0:15], v[108:111], v[112:115], v[0:15]
	s_waitcnt vmcnt(6)
	v_mfma_f32_32x32x16_bf16 v[0:15], v[116:119], v[120:123], v[0:15]
	s_waitcnt vmcnt(4)
	v_mfma_f32_32x32x16_bf16 v[0:15], v[124:127], v[128:131], v[0:15]
	s_waitcnt vmcnt(2)
	v_mfma_f32_32x32x16_bf16 v[0:15], v[132:135], v[152:155], v[0:15]
	s_waitcnt vmcnt(0)
	v_mfma_f32_32x32x16_bf16 v[0:15], v[156:159], v[168:171], v[0:15]
	s_nop 11
	ds_write2st64_b32 v24, v0, v1 offset1:1
	ds_write2st64_b32 v24, v2, v3 offset0:2 offset1:3
	ds_write2st64_b32 v24, v4, v5 offset0:4 offset1:5
	ds_write2st64_b32 v24, v6, v7 offset0:6 offset1:7
	ds_write2st64_b32 v24, v8, v9 offset0:8 offset1:9
	ds_write2st64_b32 v24, v10, v11 offset0:10 offset1:11
	ds_write2st64_b32 v24, v12, v13 offset0:12 offset1:13
	ds_write2st64_b32 v24, v14, v15 offset0:14 offset1:15
	s_waitcnt lgkmcnt(0)
	s_barrier
	s_cbranch_vccnz .LBB0_800
	v_or_b32_e32 v0, 0x4000, v28
	v_or_b32_e32 v2, s10, v22
	v_lshlrev_b32_e32 v16, 11, v0
	v_lshl_add_u64 v[4:5], s[74:75], 0, v[16:17]
	v_ashrrev_i32_e32 v3, 31, v2
	v_lshl_add_u64 v[6:7], v[2:3], 1, v[4:5]
	global_load_dwordx2 v[2:3], v[6:7], off
	global_load_dwordx2 v[4:5], v[6:7], off offset:16
	ds_read2st64_b32 v[8:9], v23 offset1:1
	ds_read2st64_b32 v[10:11], v23 offset0:2 offset1:3
	ds_read2st64_b32 v[12:13], v23 offset0:4 offset1:5
	ds_read2st64_b32 v[14:15], v23 offset0:6 offset1:7
	ds_read2st64_b32 v[28:29], v23 offset0:16 offset1:17
	ds_read2st64_b32 v[30:31], v23 offset0:18 offset1:19
	ds_read2st64_b32 v[32:33], v23 offset0:20 offset1:21
	ds_read2st64_b32 v[34:35], v23 offset0:22 offset1:23
	ds_read2st64_b32 v[36:37], v23 offset0:32 offset1:33
	ds_read2st64_b32 v[38:39], v23 offset0:34 offset1:35
	ds_read2st64_b32 v[40:41], v23 offset0:36 offset1:37
	ds_read2st64_b32 v[42:43], v23 offset0:38 offset1:39
	ds_read2st64_b32 v[44:45], v23 offset0:48 offset1:49
	ds_read2st64_b32 v[46:47], v23 offset0:50 offset1:51
	ds_read2st64_b32 v[48:49], v23 offset0:52 offset1:53
	ds_read2st64_b32 v[50:51], v23 offset0:54 offset1:55
	ds_read2st64_b32 v[52:53], v23 offset0:64 offset1:65
	ds_read2st64_b32 v[54:55], v23 offset0:66 offset1:67
	ds_read2st64_b32 v[56:57], v23 offset0:68 offset1:69
	ds_read2st64_b32 v[58:59], v23 offset0:70 offset1:71
	ds_read2st64_b32 v[60:61], v23 offset0:80 offset1:81
	ds_read2st64_b32 v[62:63], v23 offset0:82 offset1:83
	ds_read2st64_b32 v[64:65], v23 offset0:84 offset1:85
	ds_read2st64_b32 v[66:67], v23 offset0:86 offset1:87
	ds_read2st64_b32 v[68:69], v23 offset0:96 offset1:97
	ds_read2st64_b32 v[70:71], v23 offset0:98 offset1:99
	ds_read2st64_b32 v[72:73], v23 offset0:100 offset1:101
	ds_read2st64_b32 v[74:75], v23 offset0:102 offset1:103
	ds_read2st64_b32 v[76:77], v23 offset0:112 offset1:113
	ds_read2st64_b32 v[78:79], v23 offset0:114 offset1:115
	ds_read2st64_b32 v[80:81], v23 offset0:116 offset1:117
	ds_read2st64_b32 v[82:83], v23 offset0:118 offset1:119
	s_waitcnt lgkmcnt(14)
	v_pk_add_f32 v[10:11], v[10:11], 0 op_sel_hi:[1,0]
	v_pk_add_f32 v[8:9], v[8:9], 0 op_sel_hi:[1,0]
	v_pk_add_f32 v[14:15], v[14:15], 0 op_sel_hi:[1,0]
	v_pk_add_f32 v[8:9], v[8:9], v[28:29]
	v_pk_add_f32 v[10:11], v[10:11], v[30:31]
	v_pk_add_f32 v[14:15], v[14:15], v[34:35]
	v_pk_add_f32 v[10:11], v[10:11], v[38:39]
	v_pk_add_f32 v[8:9], v[8:9], v[36:37]
	v_pk_add_f32 v[12:13], v[12:13], 0 op_sel_hi:[1,0]
	v_pk_add_f32 v[14:15], v[14:15], v[42:43]
	v_pk_add_f32 v[8:9], v[8:9], v[44:45]
	v_pk_add_f32 v[10:11], v[10:11], v[46:47]
	v_pk_add_f32 v[12:13], v[12:13], v[32:33]
	v_pk_add_f32 v[14:15], v[14:15], v[50:51]
	v_pk_add_f32 v[10:11], v[10:11], v[54:55]
	v_pk_add_f32 v[8:9], v[8:9], v[52:53]
	v_pk_add_f32 v[12:13], v[12:13], v[40:41]
	s_waitcnt lgkmcnt(12)
	v_pk_add_f32 v[14:15], v[14:15], v[58:59]
	s_waitcnt lgkmcnt(11)
	v_pk_add_f32 v[8:9], v[8:9], v[60:61]
	s_waitcnt lgkmcnt(10)
	v_pk_add_f32 v[10:11], v[10:11], v[62:63]
	v_pk_add_f32 v[12:13], v[12:13], v[48:49]
	s_waitcnt lgkmcnt(8)
	v_pk_add_f32 v[14:15], v[14:15], v[66:67]
	s_waitcnt lgkmcnt(6)
	v_pk_add_f32 v[10:11], v[10:11], v[70:71]
	v_pk_add_f32 v[8:9], v[8:9], v[68:69]
	v_pk_add_f32 v[12:13], v[12:13], v[56:57]
	s_waitcnt lgkmcnt(4)
	v_pk_add_f32 v[14:15], v[14:15], v[74:75]
	s_waitcnt lgkmcnt(3)
	v_pk_add_f32 v[8:9], v[8:9], v[76:77]
	s_waitcnt lgkmcnt(2)
	v_pk_add_f32 v[10:11], v[10:11], v[78:79]
	v_pk_add_f32 v[12:13], v[12:13], v[64:65]
	s_waitcnt lgkmcnt(0)
	v_pk_add_f32 v[14:15], v[14:15], v[82:83]
	v_pk_add_f32 v[12:13], v[12:13], v[72:73]
	v_cmp_lt_i32_e32 vcc, v26, v27
	v_pk_add_f32 v[12:13], v[12:13], v[80:81]
	s_waitcnt vmcnt(1)
	v_lshlrev_b32_e32 v28, 16, v2
	v_and_b32_e32 v29, 0xffff0000, v2
	v_lshlrev_b32_e32 v2, 16, v3
	v_and_b32_e32 v3, 0xffff0000, v3
	s_waitcnt vmcnt(0)
	v_lshlrev_b32_e32 v30, 16, v4
	v_and_b32_e32 v31, 0xffff0000, v4
	v_lshlrev_b32_e32 v4, 16, v5
	v_and_b32_e32 v5, 0xffff0000, v5
	v_pk_fma_f32 v[2:3], v[2:3], s[8:9], v[10:11] op_sel_hi:[1,0,1]
	v_pk_fma_f32 v[8:9], v[28:29], s[8:9], v[8:9] op_sel_hi:[1,0,1]
	v_pk_fma_f32 v[10:11], v[4:5], s[8:9], v[14:15] op_sel_hi:[1,0,1]
	v_add_f32_e32 v1, v8, v9
	v_add_f32_e32 v4, v2, v3
	v_cvt_pk_bf16_f32 v14, v8, v9
	v_cvt_pk_bf16_f32 v15, v2, v3
	v_add_f32_e32 v1, v1, v4
	v_mul_f32_e32 v4, v9, v9
	v_mul_f32_e32 v3, v3, v3
	v_pk_fma_f32 v[12:13], v[30:31], s[8:9], v[12:13] op_sel_hi:[1,0,1]
	v_fmac_f32_e32 v4, v8, v8
	v_fmac_f32_e32 v3, v2, v2
	v_add_f32_e32 v2, v4, v3
	v_add_f32_e32 v3, v12, v13
	v_add_f32_e32 v4, v10, v11
	v_add_f32_e32 v1, 0, v1
	v_add_f32_e32 v3, v3, v4
	v_add_f32_e32 v1, v1, v3
	v_mul_f32_e32 v3, v13, v13
	v_mul_f32_e32 v4, v11, v11
	v_fmac_f32_e32 v3, v12, v12
	v_fmac_f32_e32 v4, v10, v10
	v_add_f32_e32 v3, v3, v4
	v_add_f32_e32 v2, v2, v3
	v_cndmask_b32_e32 v3, v25, v26, vcc
	v_lshlrev_b32_e32 v4, 2, v3
	ds_bpermute_b32 v3, v4, v1
	ds_bpermute_b32 v4, v4, v2
	global_store_dwordx2 v[6:7], v[14:15], off
	v_cvt_pk_bf16_f32 v8, v12, v13
	v_cvt_pk_bf16_f32 v9, v10, v11
	global_store_dwordx2 v[6:7], v[8:9], off offset:16
	s_and_saveexec_b64 s[10:11], s[4:5]
	s_cbranch_execz .LBB0_799
	s_waitcnt lgkmcnt(1)
	v_add_f32_e32 v1, v1, v3
	v_lshlrev_b32_e32 v0, 3, v0
	s_waitcnt lgkmcnt(0)
	v_add_f32_e32 v2, v2, v4
	global_atomic_add_f32 v0, v1, s[2:3]
	global_atomic_add_f32 v0, v2, s[2:3] offset:4
	s_branch .LBB0_799

.LBB0_1121:
	s_and_b32 s0, s18, 0xffffffe0
	v_or_b32_e32 v0, s0, v230
	v_ashrrev_i32_e32 v1, 31, v0
	v_lshlrev_b64 v[0:1], 11, v[0:1]
	v_lshl_add_u64 v[30:31], v[20:21], 0, v[0:1]
	s_and_b32 s1, s19, 0xe0
	v_or_b32_e32 v28, s1, v230
	v_lshlrev_b32_e32 v16, 11, v28
	v_lshl_add_u64 v[54:55], v[18:19], 0, v[16:17]
	s_addk_i32 s17, 0xc0
	s_and_b64 vcc, exec, s[4:5]
	global_load_dwordx4 v[104:107], v[30:31], off
	global_load_dwordx4 v[108:111], v[54:55], off
	global_load_dwordx4 v[112:115], v[30:31], off offset:32
	global_load_dwordx4 v[116:119], v[54:55], off offset:32
	global_load_dwordx4 v[136:139], v[30:31], off offset:64
	global_load_dwordx4 v[140:143], v[54:55], off offset:64
	global_load_dwordx4 v[148:151], v[30:31], off offset:96
	global_load_dwordx4 v[152:155], v[54:55], off offset:96
	global_load_dwordx4 v[156:159], v[30:31], off offset:128
	global_load_dwordx4 v[164:167], v[54:55], off offset:128
	global_load_dwordx4 v[168:171], v[30:31], off offset:160
	global_load_dwordx4 v[172:175], v[54:55], off offset:160
	global_load_dwordx4 v[184:187], v[30:31], off offset:192
	global_load_dwordx4 v[188:191], v[54:55], off offset:192
	global_load_dwordx4 v[192:195], v[30:31], off offset:224
	global_load_dwordx4 v[196:199], v[54:55], off offset:224
	s_waitcnt vmcnt(14)
	v_mfma_f32_32x32x16_bf16 v[0:15], v[104:107], v[108:111], 0
	s_waitcnt vmcnt(12)
	v_mfma_f32_32x32x16_bf16 v[0:15], v[112:115], v[116:119], v[0:15]
	s_waitcnt vmcnt(10)
	v_mfma_f32_32x32x16_bf16 v[0:15], v[136:139], v[140:143], v[0:15]
	s_waitcnt vmcnt(8)
	v_mfma_f32_32x32x16_bf16 v[0:15], v[148:151], v[152:155], v[0:15]
	s_waitcnt vmcnt(6)
	v_mfma_f32_32x32x16_bf16 v[0:15], v[156:159], v[164:167], v[0:15]
	s_waitcnt vmcnt(4)
	v_mfma_f32_32x32x16_bf16 v[0:15], v[168:171], v[172:175], v[0:15]
	s_waitcnt vmcnt(2)
	v_mfma_f32_32x32x16_bf16 v[0:15], v[184:187], v[188:191], v[0:15]
	s_waitcnt vmcnt(0)
	v_mfma_f32_32x32x16_bf16 v[0:15], v[192:195], v[196:199], v[0:15]
	s_nop 11
	ds_write2st64_b32 v33, v0, v1 offset1:1
	ds_write2st64_b32 v33, v2, v3 offset0:2 offset1:3
	ds_write2st64_b32 v33, v4, v5 offset0:4 offset1:5
	ds_write2st64_b32 v33, v6, v7 offset0:6 offset1:7
	ds_write2st64_b32 v33, v8, v9 offset0:8 offset1:9
	ds_write2st64_b32 v33, v10, v11 offset0:10 offset1:11
	ds_write2st64_b32 v33, v12, v13 offset0:12 offset1:13
	ds_write2st64_b32 v33, v14, v15 offset0:14 offset1:15
	s_waitcnt lgkmcnt(0)
	s_barrier
	s_cbranch_vccnz .LBB0_1120
	v_or_b32_e32 v16, 0x4000, v28
	v_lshlrev_b32_e32 v0, 3, v16
	global_load_dwordx2 v[12:13], v0, s[2:3]
	v_or_b32_e32 v10, s0, v23
	v_ashrrev_i32_e32 v11, 31, v10
	v_readlane_b32 s10, v254, 26
	v_lshlrev_b64 v[4:5], 2, v[10:11]
	v_readlane_b32 s11, v254, 27
	v_readlane_b32 s12, v254, 28
	v_or_b32_e32 v8, 8, v10
	v_lshl_add_u64 v[0:1], s[10:11], 0, v[4:5]
	global_load_dwordx4 v[0:3], v[0:1], off
	v_readlane_b32 s13, v254, 29
	v_ashrrev_i32_e32 v9, 31, v8
	v_lshlrev_b64 v[14:15], 2, v[8:9]
	v_lshl_add_u64 v[4:5], s[12:13], 0, v[4:5]
	global_load_dwordx4 v[4:7], v[4:5], off
	v_lshl_add_u64 v[30:31], s[10:11], 0, v[14:15]
	v_lshl_add_u64 v[14:15], s[12:13], 0, v[14:15]
	global_load_dwordx4 v[34:37], v[30:31], off
	global_load_dwordx4 v[38:41], v[14:15], off
	ds_read2st64_b32 v[14:15], v32 offset1:1
	ds_read2st64_b32 v[30:31], v32 offset0:2 offset1:3
	ds_read2st64_b32 v[42:43], v32 offset0:4 offset1:5
	ds_read2st64_b32 v[44:45], v32 offset0:6 offset1:7
	ds_read2st64_b32 v[46:47], v32 offset0:16 offset1:17
	ds_read2st64_b32 v[48:49], v32 offset0:18 offset1:19
	ds_read2st64_b32 v[50:51], v32 offset0:20 offset1:21
	ds_read2st64_b32 v[52:53], v32 offset0:22 offset1:23
	ds_read2st64_b32 v[54:55], v32 offset0:32 offset1:33
	ds_read2st64_b32 v[56:57], v32 offset0:34 offset1:35
	ds_read2st64_b32 v[58:59], v32 offset0:36 offset1:37
	ds_read2st64_b32 v[60:61], v32 offset0:38 offset1:39
	ds_read2st64_b32 v[62:63], v32 offset0:48 offset1:49
	ds_read2st64_b32 v[64:65], v32 offset0:50 offset1:51
	ds_read2st64_b32 v[66:67], v32 offset0:52 offset1:53
	ds_read2st64_b32 v[68:69], v32 offset0:54 offset1:55
	ds_read2st64_b32 v[70:71], v32 offset0:64 offset1:65
	ds_read2st64_b32 v[72:73], v32 offset0:66 offset1:67
	ds_read2st64_b32 v[74:75], v32 offset0:68 offset1:69
	ds_read2st64_b32 v[76:77], v32 offset0:70 offset1:71
	ds_read2st64_b32 v[78:79], v32 offset0:80 offset1:81
	ds_read2st64_b32 v[80:81], v32 offset0:82 offset1:83
	ds_read2st64_b32 v[82:83], v32 offset0:84 offset1:85
	ds_read2st64_b32 v[84:85], v32 offset0:86 offset1:87
	ds_read2st64_b32 v[86:87], v32 offset0:96 offset1:97
	ds_read2st64_b32 v[88:89], v32 offset0:98 offset1:99
	ds_read2st64_b32 v[90:91], v32 offset0:100 offset1:101
	ds_read2st64_b32 v[92:93], v32 offset0:102 offset1:103
	ds_read2st64_b32 v[94:95], v32 offset0:112 offset1:113
	ds_read2st64_b32 v[96:97], v32 offset0:114 offset1:115
	ds_read2st64_b32 v[98:99], v32 offset0:116 offset1:117
	ds_read2st64_b32 v[100:101], v32 offset0:118 offset1:119
	s_waitcnt lgkmcnt(14)
	v_pk_add_f32 v[14:15], v[14:15], 0 op_sel_hi:[1,0]
	v_pk_add_f32 v[30:31], v[30:31], 0 op_sel_hi:[1,0]
	v_pk_add_f32 v[14:15], v[14:15], v[46:47]
	v_pk_add_f32 v[30:31], v[30:31], v[48:49]
	v_pk_add_f32 v[42:43], v[42:43], 0 op_sel_hi:[1,0]
	v_pk_add_f32 v[44:45], v[44:45], 0 op_sel_hi:[1,0]
	v_pk_add_f32 v[14:15], v[14:15], v[54:55]
	v_pk_add_f32 v[30:31], v[30:31], v[56:57]
	v_pk_add_f32 v[44:45], v[44:45], v[52:53]
	v_pk_add_f32 v[42:43], v[42:43], v[50:51]
	v_pk_add_f32 v[30:31], v[30:31], v[64:65]
	v_pk_add_f32 v[14:15], v[14:15], v[62:63]
	v_pk_add_f32 v[42:43], v[42:43], v[58:59]
	v_pk_add_f32 v[44:45], v[44:45], v[60:61]
	v_pk_add_f32 v[14:15], v[14:15], v[70:71]
	v_pk_add_f32 v[30:31], v[30:31], v[72:73]
	v_pk_add_f32 v[44:45], v[44:45], v[68:69]
	v_pk_add_f32 v[42:43], v[42:43], v[66:67]
	s_waitcnt lgkmcnt(10)
	v_pk_add_f32 v[30:31], v[30:31], v[80:81]
	v_pk_add_f32 v[14:15], v[14:15], v[78:79]
	v_pk_add_f32 v[42:43], v[42:43], v[74:75]
	v_pk_add_f32 v[44:45], v[44:45], v[76:77]
	s_waitcnt lgkmcnt(7)
	v_pk_add_f32 v[14:15], v[14:15], v[86:87]
	s_waitcnt lgkmcnt(6)
	v_pk_add_f32 v[30:31], v[30:31], v[88:89]
	v_pk_add_f32 v[44:45], v[44:45], v[84:85]
	v_pk_add_f32 v[42:43], v[42:43], v[82:83]
	s_waitcnt lgkmcnt(2)
	v_pk_add_f32 v[30:31], v[30:31], v[96:97]
	v_pk_add_f32 v[14:15], v[14:15], v[94:95]
	v_pk_add_f32 v[42:43], v[42:43], v[90:91]
	v_pk_add_f32 v[44:45], v[44:45], v[92:93]
	s_and_b32 s1, s17, 0x1fffffe0
	s_cmpk_eq_i32 s1, 0x200
	s_cselect_b64 s[10:11], -1, 0
	s_waitcnt vmcnt(4)
	v_pk_mul_f32 v[46:47], v[12:13], s[8:9] op_sel_hi:[1,0]
	s_nop 0
	v_fma_f32 v9, -v46, v46, v47
	v_max_f32_e32 v9, 0, v9
	v_add_f32_e32 v9, 0x3727c5ac, v9
	v_mul_f32_e32 v12, 0x4b800000, v9
	v_cmp_gt_f32_e32 vcc, s20, v9
	s_waitcnt vmcnt(3)
	v_xor_b32_e32 v3, 0x80000000, v3
	v_cndmask_b32_e32 v9, v9, v12, vcc
	v_rsq_f32_e32 v9, v9
	v_xor_b32_e32 v2, 0x80000000, v2
	v_pk_fma_f32 v[0:1], v[0:1], v[46:47], v[14:15] op_sel_hi:[1,0,1] neg_lo:[1,0,0] neg_hi:[1,0,0]
	v_pk_fma_f32 v[2:3], v[2:3], v[46:47], v[30:31] op_sel_hi:[1,0,1]
	v_mul_f32_e32 v12, 0x45800000, v9
	v_cndmask_b32_e32 v30, v9, v12, vcc
	s_waitcnt vmcnt(2)
	v_pk_fma_f32 v[12:13], v[2:3], v[30:31], v[6:7] op_sel_hi:[1,0,1]
	v_pk_fma_f32 v[14:15], v[0:1], v[30:31], v[4:5] op_sel_hi:[1,0,1]
	s_waitcnt lgkmcnt(0)
	v_pk_add_f32 v[0:1], v[44:45], v[100:101]
	v_pk_add_f32 v[2:3], v[42:43], v[98:99]
	s_waitcnt vmcnt(1)
	v_pk_fma_f32 v[0:1], v[46:47], v[36:37], v[0:1] op_sel_hi:[0,1,1] neg_lo:[1,0,0] neg_hi:[1,0,0]
	v_pk_fma_f32 v[4:5], v[46:47], v[34:35], v[2:3] op_sel_hi:[0,1,1] neg_lo:[1,0,0] neg_hi:[1,0,0]
	s_waitcnt vmcnt(0)
	v_pk_fma_f32 v[2:3], v[0:1], v[30:31], v[40:41] op_sel_hi:[1,0,1]
	v_pk_fma_f32 v[0:1], v[4:5], v[30:31], v[38:39] op_sel_hi:[1,0,1]
	v_cmp_gt_i32_e32 vcc, s21, v10
	v_bitop3_b32 v4, s0, 48, v23 bitop3:0xc8
	s_or_b64 s[12:13], s[10:11], vcc
	v_cmp_eq_u32_e64 s[0:1], 0, v4
	s_and_b64 s[14:15], s[0:1], s[12:13]
	v_mov_b32_e32 v4, v14
	v_mov_b32_e32 v5, v15
	v_mov_b32_e32 v6, v12
	v_mov_b32_e32 v7, v13
	v_mov_b32_e32 v9, v14
	v_mov_b32_e32 v35, v15
	v_mov_b32_e32 v34, v12
	v_mov_b32_e32 v36, v13
	s_and_saveexec_b64 s[12:13], s[14:15]
	s_cbranch_execz .LBB0_1124
	global_load_dwordx4 v[4:7], v[26:27], off
	global_load_dwordx4 v[34:37], v[26:27], off offset:16
	s_waitcnt vmcnt(1)
	v_mov_b32_e32 v31, v6
	v_mov_b32_e32 v6, v5
	s_waitcnt vmcnt(0)
	v_mov_b32_e32 v39, v36
	v_mov_b32_e32 v36, v35
	v_mov_b32_e32 v30, v4
	v_mov_b32_e32 v38, v34
	v_pk_mul_f32 v[4:5], v[0:1], v[6:7]
	v_pk_mul_f32 v[6:7], v[2:3], v[36:37]
	v_pk_fma_f32 v[4:5], v[14:15], v[30:31], v[4:5] neg_lo:[0,0,1] neg_hi:[0,0,1]
	v_pk_fma_f32 v[6:7], v[12:13], v[38:39], v[6:7] neg_lo:[0,0,1] neg_hi:[0,0,1]
	v_mov_b32_e32 v9, v4
	v_mov_b32_e32 v35, v5
	v_mov_b32_e32 v34, v6
	v_mov_b32_e32 v36, v7

.LBB0_1135:
	s_and_b32 s0, s15, 0xffffffe0
	v_or_b32_e32 v0, s0, v230
	v_ashrrev_i32_e32 v1, 31, v0
	v_lshlrev_b64 v[0:1], 11, v[0:1]
	v_lshl_add_u64 v[54:55], v[20:21], 0, v[0:1]
	s_and_b32 s1, s16, 0xe0
	v_or_b32_e32 v28, s1, v230
	v_lshlrev_b32_e32 v16, 11, v28
	v_lshl_add_u64 v[56:57], v[18:19], 0, v[16:17]
	s_and_b64 vcc, exec, s[4:5]
	global_load_dwordx4 v[104:107], v[54:55], off
	global_load_dwordx4 v[108:111], v[56:57], off
	global_load_dwordx4 v[112:115], v[54:55], off offset:32
	global_load_dwordx4 v[116:119], v[56:57], off offset:32
	global_load_dwordx4 v[136:139], v[54:55], off offset:64
	global_load_dwordx4 v[140:143], v[56:57], off offset:64
	global_load_dwordx4 v[148:151], v[54:55], off offset:96
	global_load_dwordx4 v[152:155], v[56:57], off offset:96
	global_load_dwordx4 v[156:159], v[54:55], off offset:128
	global_load_dwordx4 v[164:167], v[56:57], off offset:128
	global_load_dwordx4 v[168:171], v[54:55], off offset:160
	global_load_dwordx4 v[172:175], v[56:57], off offset:160
	global_load_dwordx4 v[184:187], v[54:55], off offset:192
	global_load_dwordx4 v[188:191], v[56:57], off offset:192
	global_load_dwordx4 v[192:195], v[54:55], off offset:224
	global_load_dwordx4 v[196:199], v[56:57], off offset:224
	s_waitcnt vmcnt(14)
	v_mfma_f32_32x32x16_bf16 v[0:15], v[104:107], v[108:111], 0
	s_waitcnt vmcnt(12)
	v_mfma_f32_32x32x16_bf16 v[0:15], v[112:115], v[116:119], v[0:15]
	s_waitcnt vmcnt(10)
	v_mfma_f32_32x32x16_bf16 v[0:15], v[136:139], v[140:143], v[0:15]
	s_waitcnt vmcnt(8)
	v_mfma_f32_32x32x16_bf16 v[0:15], v[148:151], v[152:155], v[0:15]
	s_waitcnt vmcnt(6)
	v_mfma_f32_32x32x16_bf16 v[0:15], v[156:159], v[164:167], v[0:15]
	s_waitcnt vmcnt(4)
	v_mfma_f32_32x32x16_bf16 v[0:15], v[168:171], v[172:175], v[0:15]
	s_waitcnt vmcnt(2)
	v_mfma_f32_32x32x16_bf16 v[0:15], v[184:187], v[188:191], v[0:15]
	s_waitcnt vmcnt(0)
	v_mfma_f32_32x32x16_bf16 v[0:15], v[192:195], v[196:199], v[0:15]
	s_nop 11
	ds_write2st64_b32 v35, v0, v1 offset1:1
	ds_write2st64_b32 v35, v2, v3 offset0:2 offset1:3
	ds_write2st64_b32 v35, v4, v5 offset0:4 offset1:5
	ds_write2st64_b32 v35, v6, v7 offset0:6 offset1:7
	ds_write2st64_b32 v35, v8, v9 offset0:8 offset1:9
	ds_write2st64_b32 v35, v10, v11 offset0:10 offset1:11
	ds_write2st64_b32 v35, v12, v13 offset0:12 offset1:13
	ds_write2st64_b32 v35, v14, v15 offset0:14 offset1:15
	s_waitcnt lgkmcnt(0)
	s_barrier
	s_cbranch_vccnz .LBB0_1134
	v_or_b32_e32 v16, 0x4000, v28
	v_lshlrev_b32_e32 v0, 3, v16
	global_load_dwordx2 v[12:13], v0, s[2:3]
	v_add_u32_e32 v10, s0, v34
	v_ashrrev_i32_e32 v11, 31, v10
	v_readlane_b32 s0, v254, 26
	v_lshlrev_b64 v[4:5], 2, v[10:11]
	v_readlane_b32 s1, v254, 27
	v_readlane_b32 s6, v254, 28
	v_or_b32_e32 v8, 8, v10
	v_lshl_add_u64 v[0:1], s[0:1], 0, v[4:5]
	global_load_dwordx4 v[0:3], v[0:1], off
	v_readlane_b32 s7, v254, 29
	v_ashrrev_i32_e32 v9, 31, v8
	v_lshlrev_b64 v[14:15], 2, v[8:9]
	v_lshl_add_u64 v[4:5], s[6:7], 0, v[4:5]
	global_load_dwordx4 v[4:7], v[4:5], off
	v_lshl_add_u64 v[30:31], s[0:1], 0, v[14:15]
	v_lshl_add_u64 v[14:15], s[6:7], 0, v[14:15]
	global_load_dwordx4 v[30:33], v[30:31], off
	s_nop 0
	global_load_dwordx4 v[38:41], v[14:15], off
	ds_read2st64_b32 v[14:15], v23 offset1:1
	ds_read2st64_b32 v[42:43], v23 offset0:2 offset1:3
	ds_read2st64_b32 v[44:45], v23 offset0:4 offset1:5
	ds_read2st64_b32 v[46:47], v23 offset0:6 offset1:7
	ds_read2st64_b32 v[48:49], v23 offset0:16 offset1:17
	ds_read2st64_b32 v[50:51], v23 offset0:18 offset1:19
	ds_read2st64_b32 v[52:53], v23 offset0:20 offset1:21
	ds_read2st64_b32 v[54:55], v23 offset0:22 offset1:23
	ds_read2st64_b32 v[56:57], v23 offset0:32 offset1:33
	ds_read2st64_b32 v[58:59], v23 offset0:34 offset1:35
	ds_read2st64_b32 v[60:61], v23 offset0:36 offset1:37
	ds_read2st64_b32 v[62:63], v23 offset0:38 offset1:39
	ds_read2st64_b32 v[64:65], v23 offset0:48 offset1:49
	ds_read2st64_b32 v[66:67], v23 offset0:50 offset1:51
	ds_read2st64_b32 v[68:69], v23 offset0:52 offset1:53
	ds_read2st64_b32 v[70:71], v23 offset0:54 offset1:55
	ds_read2st64_b32 v[72:73], v23 offset0:64 offset1:65
	ds_read2st64_b32 v[74:75], v23 offset0:66 offset1:67
	ds_read2st64_b32 v[76:77], v23 offset0:68 offset1:69
	ds_read2st64_b32 v[78:79], v23 offset0:70 offset1:71
	ds_read2st64_b32 v[80:81], v23 offset0:80 offset1:81
	ds_read2st64_b32 v[82:83], v23 offset0:82 offset1:83
	ds_read2st64_b32 v[84:85], v23 offset0:84 offset1:85
	ds_read2st64_b32 v[86:87], v23 offset0:86 offset1:87
	ds_read2st64_b32 v[88:89], v23 offset0:96 offset1:97
	ds_read2st64_b32 v[90:91], v23 offset0:98 offset1:99
	ds_read2st64_b32 v[92:93], v23 offset0:100 offset1:101
	ds_read2st64_b32 v[94:95], v23 offset0:102 offset1:103
	ds_read2st64_b32 v[96:97], v23 offset0:112 offset1:113
	ds_read2st64_b32 v[98:99], v23 offset0:114 offset1:115
	ds_read2st64_b32 v[100:101], v23 offset0:116 offset1:117
	ds_read2st64_b32 v[102:103], v23 offset0:118 offset1:119
	s_waitcnt lgkmcnt(14)
	v_pk_add_f32 v[14:15], v[14:15], 0 op_sel_hi:[1,0]
	v_pk_add_f32 v[42:43], v[42:43], 0 op_sel_hi:[1,0]
	v_pk_add_f32 v[14:15], v[14:15], v[48:49]
	v_pk_add_f32 v[42:43], v[42:43], v[50:51]
	v_pk_add_f32 v[44:45], v[44:45], 0 op_sel_hi:[1,0]
	v_pk_add_f32 v[46:47], v[46:47], 0 op_sel_hi:[1,0]
	v_pk_add_f32 v[14:15], v[14:15], v[56:57]
	v_pk_add_f32 v[42:43], v[42:43], v[58:59]
	v_pk_add_f32 v[46:47], v[46:47], v[54:55]
	v_pk_add_f32 v[44:45], v[44:45], v[52:53]
	v_pk_add_f32 v[42:43], v[42:43], v[66:67]
	v_pk_add_f32 v[14:15], v[14:15], v[64:65]
	v_pk_add_f32 v[44:45], v[44:45], v[60:61]
	v_pk_add_f32 v[46:47], v[46:47], v[62:63]
	v_pk_add_f32 v[14:15], v[14:15], v[72:73]
	v_pk_add_f32 v[42:43], v[42:43], v[74:75]
	v_pk_add_f32 v[46:47], v[46:47], v[70:71]
	v_pk_add_f32 v[44:45], v[44:45], v[68:69]
	s_waitcnt lgkmcnt(10)
	v_pk_add_f32 v[42:43], v[42:43], v[82:83]
	v_pk_add_f32 v[14:15], v[14:15], v[80:81]
	v_pk_add_f32 v[44:45], v[44:45], v[76:77]
	v_pk_add_f32 v[46:47], v[46:47], v[78:79]
	s_waitcnt lgkmcnt(7)
	v_pk_add_f32 v[14:15], v[14:15], v[88:89]
	s_waitcnt lgkmcnt(6)
	v_pk_add_f32 v[42:43], v[42:43], v[90:91]
	v_pk_add_f32 v[46:47], v[46:47], v[86:87]
	v_pk_add_f32 v[44:45], v[44:45], v[84:85]
	s_waitcnt lgkmcnt(2)
	v_pk_add_f32 v[42:43], v[42:43], v[98:99]
	v_pk_add_f32 v[14:15], v[14:15], v[96:97]
	v_pk_add_f32 v[44:45], v[44:45], v[92:93]
	v_pk_add_f32 v[46:47], v[46:47], v[94:95]
	s_waitcnt vmcnt(4)
	v_pk_mul_f32 v[48:49], v[12:13], s[10:11] op_sel_hi:[1,0]
	s_nop 0
	v_fma_f32 v9, -v48, v48, v49
	v_max_f32_e32 v9, 0, v9
	v_add_f32_e32 v9, 0x3727c5ac, v9
	v_mul_f32_e32 v12, 0x4b800000, v9
	v_cmp_gt_f32_e32 vcc, s17, v9
	s_waitcnt vmcnt(3)
	v_xor_b32_e32 v3, 0x80000000, v3
	v_cndmask_b32_e32 v9, v9, v12, vcc
	v_rsq_f32_e32 v9, v9
	v_xor_b32_e32 v2, 0x80000000, v2
	v_pk_fma_f32 v[0:1], v[0:1], v[48:49], v[14:15] op_sel_hi:[1,0,1] neg_lo:[1,0,0] neg_hi:[1,0,0]
	v_pk_fma_f32 v[2:3], v[2:3], v[48:49], v[42:43] op_sel_hi:[1,0,1]
	v_mul_f32_e32 v12, 0x45800000, v9
	v_cndmask_b32_e32 v42, v9, v12, vcc
	s_waitcnt vmcnt(2)
	v_pk_fma_f32 v[12:13], v[2:3], v[42:43], v[6:7] op_sel_hi:[1,0,1]
	v_pk_fma_f32 v[14:15], v[0:1], v[42:43], v[4:5] op_sel_hi:[1,0,1]
	s_waitcnt lgkmcnt(0)
	v_pk_add_f32 v[0:1], v[46:47], v[102:103]
	v_pk_add_f32 v[2:3], v[44:45], v[100:101]
	s_waitcnt vmcnt(1)
	v_pk_fma_f32 v[0:1], v[48:49], v[32:33], v[0:1] op_sel_hi:[0,1,1] neg_lo:[1,0,0] neg_hi:[1,0,0]
	v_pk_fma_f32 v[4:5], v[48:49], v[30:31], v[2:3] op_sel_hi:[0,1,1] neg_lo:[1,0,0] neg_hi:[1,0,0]
	s_waitcnt vmcnt(0)
	v_pk_fma_f32 v[2:3], v[0:1], v[42:43], v[40:41] op_sel_hi:[1,0,1]
	v_pk_fma_f32 v[0:1], v[4:5], v[42:43], v[38:39] op_sel_hi:[1,0,1]
	v_and_b32_e32 v4, 0x7fffff80, v10
	v_cmp_gt_i32_e32 vcc, s18, v10
	v_cmp_eq_u32_e64 s[6:7], s11, v4
	v_and_b32_e32 v4, 48, v10
	s_or_b64 s[0:1], vcc, s[6:7]
	v_cmp_eq_u32_e64 s[8:9], 0, v4
	s_and_b64 s[12:13], s[8:9], s[0:1]
	v_mov_b32_e32 v4, v14
	v_mov_b32_e32 v5, v15
	v_mov_b32_e32 v6, v12
	v_mov_b32_e32 v7, v13
	v_mov_b32_e32 v9, v14
	v_mov_b32_e32 v39, v15
	v_mov_b32_e32 v38, v12
	v_mov_b32_e32 v40, v13
	s_and_saveexec_b64 s[0:1], s[12:13]
	s_cbranch_execz .LBB0_1138
	global_load_dwordx4 v[4:7], v[26:27], off
	global_load_dwordx4 v[30:33], v[26:27], off offset:16
	s_waitcnt vmcnt(1)
	v_mov_b32_e32 v39, v6
	v_mov_b32_e32 v6, v5
	s_waitcnt vmcnt(0)
	v_mov_b32_e32 v41, v32
	v_mov_b32_e32 v32, v31
	v_mov_b32_e32 v38, v4
	v_mov_b32_e32 v40, v30
	v_pk_mul_f32 v[4:5], v[0:1], v[6:7]
	v_pk_mul_f32 v[6:7], v[2:3], v[32:33]
	v_pk_fma_f32 v[4:5], v[14:15], v[38:39], v[4:5] neg_lo:[0,0,1] neg_hi:[0,0,1]
	v_pk_fma_f32 v[6:7], v[12:13], v[40:41], v[6:7] neg_lo:[0,0,1] neg_hi:[0,0,1]
	v_mov_b32_e32 v9, v4
	v_mov_b32_e32 v39, v5
	v_mov_b32_e32 v38, v6
	v_mov_b32_e32 v40, v7

.LBB0_1514:
	s_and_b32 s16, s9, 0xffffffe0
	v_or_b32_e32 v0, s16, v230
	v_ashrrev_i32_e32 v1, 31, v0
	v_lshlrev_b64 v[0:1], 11, v[0:1]
	v_lshl_add_u64 v[50:51], v[20:21], 0, v[0:1]
	s_and_b32 s17, s18, 0xe0
	v_or_b32_e32 v28, s17, v230
	v_lshlrev_b32_e32 v16, 11, v28
	v_lshl_add_u64 v[52:53], v[18:19], 0, v[16:17]
	s_and_b64 vcc, exec, s[6:7]
	global_load_dwordx4 v[104:107], v[50:51], off
	global_load_dwordx4 v[108:111], v[52:53], off
	global_load_dwordx4 v[112:115], v[50:51], off offset:32
	global_load_dwordx4 v[116:119], v[52:53], off offset:32
	global_load_dwordx4 v[120:123], v[50:51], off offset:64
	global_load_dwordx4 v[124:127], v[52:53], off offset:64
	global_load_dwordx4 v[128:131], v[50:51], off offset:96
	global_load_dwordx4 v[132:135], v[52:53], off offset:96
	global_load_dwordx4 v[136:139], v[50:51], off offset:128
	global_load_dwordx4 v[140:143], v[52:53], off offset:128
	global_load_dwordx4 v[144:147], v[50:51], off offset:160
	global_load_dwordx4 v[148:151], v[52:53], off offset:160
	global_load_dwordx4 v[152:155], v[50:51], off offset:192
	global_load_dwordx4 v[156:159], v[52:53], off offset:192
	global_load_dwordx4 v[160:163], v[50:51], off offset:224
	global_load_dwordx4 v[164:167], v[52:53], off offset:224
	s_waitcnt vmcnt(14)
	v_mfma_f32_32x32x16_bf16 v[0:15], v[104:107], v[108:111], 0
	s_waitcnt vmcnt(12)
	v_mfma_f32_32x32x16_bf16 v[0:15], v[112:115], v[116:119], v[0:15]
	s_waitcnt vmcnt(10)
	v_mfma_f32_32x32x16_bf16 v[0:15], v[120:123], v[124:127], v[0:15]
	s_waitcnt vmcnt(8)
	v_mfma_f32_32x32x16_bf16 v[0:15], v[128:131], v[132:135], v[0:15]
	s_waitcnt vmcnt(6)
	v_mfma_f32_32x32x16_bf16 v[0:15], v[136:139], v[140:143], v[0:15]
	s_waitcnt vmcnt(4)
	v_mfma_f32_32x32x16_bf16 v[0:15], v[144:147], v[148:151], v[0:15]
	s_waitcnt vmcnt(2)
	v_mfma_f32_32x32x16_bf16 v[0:15], v[152:155], v[156:159], v[0:15]
	s_waitcnt vmcnt(0)
	v_mfma_f32_32x32x16_bf16 v[0:15], v[160:163], v[164:167], v[0:15]
	s_nop 11
	ds_write2st64_b32 v24, v0, v1 offset1:1
	ds_write2st64_b32 v24, v2, v3 offset0:2 offset1:3
	ds_write2st64_b32 v24, v4, v5 offset0:4 offset1:5
	ds_write2st64_b32 v24, v6, v7 offset0:6 offset1:7
	ds_write2st64_b32 v24, v8, v9 offset0:8 offset1:9
	ds_write2st64_b32 v24, v10, v11 offset0:10 offset1:11
	ds_write2st64_b32 v24, v12, v13 offset0:12 offset1:13
	ds_write2st64_b32 v24, v14, v15 offset0:14 offset1:15
	s_waitcnt lgkmcnt(0)
	s_barrier
	s_cbranch_vccnz .LBB0_1513
	v_or_b32_e32 v1, 0x4000, v28
	v_lshlrev_b32_e32 v0, 3, v1
	v_or_b32_e32 v4, s16, v22
	global_load_dwordx2 v[32:33], v0, s[2:3]
	v_lshlrev_b32_e32 v16, 11, v1
	v_ashrrev_i32_e32 v5, 31, v4
	v_lshl_add_u64 v[6:7], s[74:75], 0, v[16:17]
	v_lshlrev_b64 v[2:3], 1, v[4:5]
	v_lshl_add_u64 v[12:13], v[6:7], 0, v[2:3]
	global_load_dwordx2 v[34:35], v[12:13], off
	v_lshlrev_b64 v[4:5], 2, v[4:5]
	v_lshl_add_u64 v[36:37], s[80:81], 0, v[4:5]
	v_lshl_add_u64 v[38:39], s[82:83], 0, v[4:5]
	global_load_dwordx4 v[4:7], v[36:37], off
	global_load_dwordx4 v[8:11], v[38:39], off
	ds_read2st64_b32 v[40:41], v23 offset1:1
	ds_read2st64_b32 v[42:43], v23 offset0:2 offset1:3
	ds_read2st64_b32 v[44:45], v23 offset0:4 offset1:5
	ds_read2st64_b32 v[46:47], v23 offset0:6 offset1:7
	ds_read2st64_b32 v[48:49], v23 offset0:16 offset1:17
	ds_read2st64_b32 v[50:51], v23 offset0:18 offset1:19
	ds_read2st64_b32 v[52:53], v23 offset0:20 offset1:21
	ds_read2st64_b32 v[54:55], v23 offset0:22 offset1:23
	global_load_dwordx2 v[56:57], v[12:13], off offset:16
	ds_read2st64_b32 v[58:59], v23 offset0:32 offset1:33
	ds_read2st64_b32 v[60:61], v23 offset0:34 offset1:35
	ds_read2st64_b32 v[62:63], v23 offset0:36 offset1:37
	ds_read2st64_b32 v[64:65], v23 offset0:38 offset1:39
	ds_read2st64_b32 v[66:67], v23 offset0:48 offset1:49
	ds_read2st64_b32 v[68:69], v23 offset0:50 offset1:51
	ds_read2st64_b32 v[70:71], v23 offset0:52 offset1:53
	ds_read2st64_b32 v[72:73], v23 offset0:54 offset1:55
	global_load_dwordx4 v[12:15], v[36:37], off offset:32
	global_load_dwordx4 v[28:31], v[38:39], off offset:32
	s_waitcnt lgkmcnt(14)
	v_pk_add_f32 v[40:41], v[40:41], 0 op_sel_hi:[1,0]
	ds_read2st64_b32 v[36:37], v23 offset0:64 offset1:65
	ds_read2st64_b32 v[38:39], v23 offset0:66 offset1:67
	ds_read2st64_b32 v[74:75], v23 offset0:68 offset1:69
	ds_read2st64_b32 v[76:77], v23 offset0:70 offset1:71
	ds_read2st64_b32 v[78:79], v23 offset0:80 offset1:81
	ds_read2st64_b32 v[80:81], v23 offset0:82 offset1:83
	ds_read2st64_b32 v[82:83], v23 offset0:84 offset1:85
	ds_read2st64_b32 v[84:85], v23 offset0:86 offset1:87
	ds_read2st64_b32 v[86:87], v23 offset0:96 offset1:97
	ds_read2st64_b32 v[88:89], v23 offset0:98 offset1:99
	ds_read2st64_b32 v[90:91], v23 offset0:100 offset1:101
	ds_read2st64_b32 v[92:93], v23 offset0:102 offset1:103
	ds_read2st64_b32 v[94:95], v23 offset0:112 offset1:113
	ds_read2st64_b32 v[96:97], v23 offset0:114 offset1:115
	ds_read2st64_b32 v[98:99], v23 offset0:116 offset1:117
	ds_read2st64_b32 v[100:101], v23 offset0:118 offset1:119
	s_waitcnt lgkmcnt(14)
	v_pk_add_f32 v[40:41], v[40:41], v[48:49]
	v_pk_add_f32 v[42:43], v[42:43], 0 op_sel_hi:[1,0]
	v_pk_add_f32 v[40:41], v[40:41], v[58:59]
	v_pk_add_f32 v[44:45], v[44:45], 0 op_sel_hi:[1,0]
	v_pk_add_f32 v[40:41], v[40:41], v[66:67]
	v_pk_add_f32 v[42:43], v[42:43], v[50:51]
	v_pk_add_f32 v[36:37], v[40:41], v[36:37]
	v_pk_add_f32 v[44:45], v[44:45], v[52:53]
	s_waitcnt lgkmcnt(11)
	v_pk_add_f32 v[36:37], v[36:37], v[78:79]
	v_pk_add_f32 v[42:43], v[42:43], v[60:61]
	v_pk_add_f32 v[44:45], v[44:45], v[62:63]
	s_waitcnt lgkmcnt(7)
	v_pk_add_f32 v[36:37], v[36:37], v[86:87]
	v_pk_add_f32 v[46:47], v[46:47], 0 op_sel_hi:[1,0]
	v_pk_add_f32 v[42:43], v[42:43], v[68:69]
	v_pk_add_f32 v[44:45], v[44:45], v[70:71]
	s_waitcnt lgkmcnt(3)
	v_pk_add_f32 v[36:37], v[36:37], v[94:95]
	v_pk_add_f32 v[46:47], v[46:47], v[54:55]
	v_pk_add_f32 v[38:39], v[42:43], v[38:39]
	v_pk_add_f32 v[46:47], v[46:47], v[64:65]
	v_pk_add_f32 v[38:39], v[38:39], v[80:81]
	s_waitcnt vmcnt(6)
	v_pk_mul_f32 v[32:33], v[32:33], s[8:9] op_sel:[1,0] op_sel_hi:[0,0]
	v_fma_f32 v1, -v33, v33, v32
	v_max_f32_e32 v1, 0, v1
	v_add_f32_e32 v1, 0x3727c5ac, v1
	v_cmp_gt_f32_e32 vcc, s20, v1
	v_pk_add_f32 v[38:39], v[38:39], v[88:89]
	s_waitcnt vmcnt(5)
	v_lshlrev_b32_e32 v32, 16, v34
	v_and_b32_e32 v34, 0xffff0000, v34
	v_lshlrev_b32_e32 v40, 16, v35
	v_and_b32_e32 v41, 0xffff0000, v35
	v_sub_f32_e32 v35, v34, v33
	v_mul_f32_e32 v34, 0x4b800000, v1
	v_cndmask_b32_e32 v1, v1, v34, vcc
	v_rsq_f32_e32 v1, v1
	v_sub_f32_e32 v34, v32, v33
	v_sub_f32_e32 v41, v41, v33
	v_sub_f32_e32 v40, v40, v33
	v_mul_f32_e32 v32, 0x45800000, v1
	v_cndmask_b32_e32 v32, v1, v32, vcc
	v_pk_mul_f32 v[34:35], v[34:35], v[32:33] op_sel_hi:[1,0]
	v_pk_mul_f32 v[40:41], v[40:41], v[32:33] op_sel_hi:[1,0]
	s_waitcnt vmcnt(3)
	v_pk_fma_f32 v[4:5], v[4:5], v[34:35], v[8:9]
	v_pk_fma_f32 v[6:7], v[6:7], v[40:41], v[10:11]
	v_pk_fma_f32 v[4:5], v[4:5], s[14:15], v[36:37] op_sel_hi:[1,0,1]
	v_pk_add_f32 v[10:11], v[44:45], v[74:75]
	s_waitcnt vmcnt(2)
	v_lshlrev_b32_e32 v1, 16, v56
	v_and_b32_e32 v34, 0xffff0000, v56
	v_lshlrev_b32_e32 v36, 16, v57
	v_and_b32_e32 v37, 0xffff0000, v57
	v_pk_add_f32 v[10:11], v[10:11], v[82:83]
	v_sub_f32_e32 v35, v34, v33
	v_sub_f32_e32 v34, v1, v33
	v_sub_f32_e32 v37, v37, v33
	v_sub_f32_e32 v36, v36, v33
	v_pk_add_f32 v[8:9], v[46:47], v[72:73]
	v_pk_add_f32 v[10:11], v[10:11], v[90:91]
	v_pk_mul_f32 v[36:37], v[36:37], v[32:33] op_sel_hi:[1,0]
	v_pk_mul_f32 v[32:33], v[34:35], v[32:33] op_sel_hi:[1,0]
	s_waitcnt lgkmcnt(2)
	v_pk_add_f32 v[38:39], v[38:39], v[96:97]
	v_pk_add_f32 v[8:9], v[8:9], v[76:77]
	s_waitcnt lgkmcnt(1)
	v_pk_add_f32 v[10:11], v[10:11], v[98:99]
	s_waitcnt vmcnt(0)
	v_pk_fma_f32 v[12:13], v[12:13], v[32:33], v[28:29]
	v_pk_fma_f32 v[6:7], v[6:7], s[14:15], v[38:39] op_sel_hi:[1,0,1]
	v_pk_add_f32 v[8:9], v[8:9], v[84:85]
	v_pk_fma_f32 v[10:11], v[12:13], s[14:15], v[10:11] op_sel_hi:[1,0,1]
	v_lshl_add_u64 v[12:13], s[12:13], 0, v[16:17]
	v_pk_add_f32 v[8:9], v[8:9], v[92:93]
	v_lshl_add_u64 v[12:13], v[12:13], 0, v[2:3]
	v_add_f32_e32 v1, v4, v5
	v_add_f32_e32 v2, v6, v7
	s_waitcnt lgkmcnt(0)
	v_pk_add_f32 v[8:9], v[8:9], v[100:101]
	v_pk_fma_f32 v[14:15], v[14:15], v[36:37], v[30:31]
	v_add_f32_e32 v1, v1, v2
	v_mul_f32_e32 v2, v5, v5
	v_mul_f32_e32 v3, v7, v7
	v_pk_fma_f32 v[8:9], v[14:15], s[14:15], v[8:9] op_sel_hi:[1,0,1]
	v_fmac_f32_e32 v2, v4, v4
	v_fmac_f32_e32 v3, v6, v6
	v_cvt_pk_bf16_f32 v14, v4, v5
	v_add_f32_e32 v3, v2, v3
	v_add_f32_e32 v2, v10, v11
	v_add_f32_e32 v4, v8, v9
	v_add_f32_e32 v1, 0, v1
	v_add_f32_e32 v2, v2, v4
	v_add_f32_e32 v2, v2, v1
	v_mul_f32_e32 v1, v11, v11
	v_mul_f32_e32 v4, v9, v9
	v_fmac_f32_e32 v1, v10, v10
	v_fmac_f32_e32 v4, v8, v8
	v_add_f32_e32 v1, v1, v4
	v_cmp_lt_i32_e32 vcc, v26, v27
	v_add_f32_e32 v3, v3, v1
	v_cvt_pk_bf16_f32 v15, v6, v7
	global_store_dwordx2 v[12:13], v[14:15], off
	v_cndmask_b32_e32 v1, v25, v26, vcc
	v_lshlrev_b32_e32 v1, 2, v1
	ds_bpermute_b32 v4, v1, v2
	ds_bpermute_b32 v5, v1, v3
	v_cvt_pk_bf16_f32 v6, v10, v11
	v_cvt_pk_bf16_f32 v7, v8, v9
	global_store_dwordx2 v[12:13], v[6:7], off offset:16
	s_and_saveexec_b64 s[16:17], s[4:5]
	s_cbranch_execz .LBB0_1512
	v_mov_b32_e32 v1, v17
	s_waitcnt lgkmcnt(1)
	v_add_f32_e32 v2, v2, v4
	v_lshl_add_u64 v[0:1], s[10:11], 0, v[0:1]
	s_waitcnt lgkmcnt(0)
	v_add_f32_e32 v3, v3, v5
	global_atomic_add_f32 v[0:1], v2, off
	global_atomic_add_f32 v[0:1], v3, off offset:4
	s_branch .LBB0_1512
